# grid barrier: acquire invalidate issued early, overlapped with arrival atomic and generation polling
# speedup vs baseline: 1.0420x; 1.0114x over previous
.LBB0_524:
	s_or_b64 exec, exec, s[2:3]
	v_cvt_f32_u32_e32 v5, v3
	s_waitcnt vmcnt(0)
	v_readfirstlane_b32 s2, v4
	v_sub_u32_e32 v4, 0, v3
	v_rcp_iflag_f32_e32 v5, v5
	v_add_u32_e32 v6, s2, v0
	v_mul_f32_e32 v5, 0x4f7ffffe, v5
	v_cvt_u32_f32_e32 v5, v5
	v_mul_lo_u32 v0, v4, v5
	v_mul_hi_u32 v0, v5, v0
	v_add_u32_e32 v0, v5, v0
	v_mul_hi_u32 v0, v6, v0
	v_mul_lo_u32 v4, v0, v3
	v_sub_u32_e32 v4, v6, v4
	v_add_u32_e32 v5, 1, v0
	v_cmp_ge_u32_e32 vcc, v4, v3
	s_nop 1
	v_cndmask_b32_e32 v0, v0, v5, vcc
	v_sub_u32_e32 v5, v4, v3
	v_cndmask_b32_e32 v4, v4, v5, vcc
	v_add_u32_e32 v5, 1, v0
	v_cmp_ge_u32_e32 vcc, v4, v3
	v_add_u32_e32 v4, 1, v6
	s_nop 0
	v_cndmask_b32_e32 v0, v0, v5, vcc
	v_mul_lo_u32 v5, v3, v0
	v_add_u32_e32 v3, v5, v3
	v_cmp_ne_u32_e32 vcc, v4, v3
	s_and_saveexec_b64 s[2:3], vcc
	s_xor_b64 s[2:3], exec, s[2:3]
	s_cbranch_execz .LBB0_538
	v_readlane_b32 s20, v253, 17
	v_readlane_b32 s21, v253, 18
	s_waitcnt lgkmcnt(0)
	s_nop 3
	global_load_dword v2, v1, s[20:21] sc1
	buffer_inv sc1
	s_waitcnt vmcnt(0)
	v_cmp_eq_u32_e32 vcc, v2, v0
	s_and_saveexec_b64 s[20:21], vcc
	s_cbranch_execz .LBB0_537
	s_mov_b32 s35, 1
	s_mov_b64 s[22:23], 0
	s_branch .LBB0_528

.LBB0_537:
	s_or_b64 exec, exec, s[20:21]
	s_waitcnt vmcnt(0)
	s_waitcnt vmcnt(0)

.LBB0_541:
	s_or_b64 exec, exec, s[20:21]
	buffer_inv sc1
	s_waitcnt vmcnt(0)
	v_readfirstlane_b32 s2, v3
	v_sub_u32_e32 v4, 0, v2
	s_mov_b64 s[20:21], -1
	v_add_u32_e32 v3, s2, v0
	v_cvt_f32_u32_e32 v0, v2
	v_readlane_b32 s2, v253, 21
	v_readlane_b32 s3, v253, 22
	v_rcp_iflag_f32_e32 v0, v0
	s_nop 0
	v_mul_f32_e32 v0, 0x4f7ffffe, v0
	v_cvt_u32_f32_e32 v0, v0
	v_mul_lo_u32 v4, v4, v0
	v_mul_hi_u32 v4, v0, v4
	v_add_u32_e32 v0, v0, v4
	v_mul_hi_u32 v0, v3, v0
	v_mul_lo_u32 v4, v0, v2
	v_sub_u32_e32 v4, v3, v4
	v_cmp_ge_u32_e32 vcc, v4, v2
	v_add_u32_e32 v5, 1, v0
	v_add_u32_e32 v3, 1, v3
	v_cndmask_b32_e32 v0, v0, v5, vcc
	v_sub_u32_e32 v5, v4, v2
	v_cndmask_b32_e32 v4, v4, v5, vcc
	v_cmp_ge_u32_e32 vcc, v4, v2
	v_add_u32_e32 v4, 1, v0
	s_nop 0
	v_cndmask_b32_e32 v0, v0, v4, vcc
	v_mul_lo_u32 v4, v2, v0
	v_add_u32_e32 v2, v4, v2
	v_cmp_ne_u32_e32 vcc, v3, v2
	v_mov_b64_e32 v[2:3], s[2:3]
	s_and_saveexec_b64 s[2:3], vcc
	s_cbranch_execz .LBB0_553
	v_readlane_b32 s20, v253, 21
	v_readlane_b32 s21, v253, 22
	s_mov_b64 s[22:23], 0
	s_nop 3
	global_load_dword v2, v1, s[20:21] sc1
	s_waitcnt vmcnt(0)
	v_cmp_eq_u32_e32 vcc, v2, v0
	s_and_saveexec_b64 s[20:21], vcc
	s_cbranch_execz .LBB0_552
	s_mov_b32 s35, 1
	s_branch .LBB0_545

.LBB0_555:
	s_or_b64 exec, exec, s[2:3]
	s_mov_b64 s[2:3], exec
	v_mbcnt_lo_u32_b32 v0, s2, 0
	v_mbcnt_hi_u32_b32 v0, s3, v0
	v_cmp_eq_u32_e32 vcc, 0, v0
	s_waitcnt vmcnt(0)
	s_and_saveexec_b64 s[20:21], vcc
	s_cbranch_execz .LBB0_557
	s_bcnt1_i32_b64 s2, s[2:3]
	v_mov_b32_e32 v0, s2
	v_readlane_b32 s2, v253, 17
	v_readlane_b32 s3, v253, 18
	s_nop 4
	s_nop 0
